# v16 with the static s_setprio 1 given to waves 4-7 (the second-dispatched half) instead of waves 0-3
# baseline (speedup 1.0000x reference)
; #define LAS __attribute__((address_space(3)))
; __global__ void __launch_bounds__(NTHR, 2) hybrid_fwd(Args args) {
;     extern __shared__ __attribute__((aligned(16))) unsigned char lds_raw[];
;     LAS unsigned char* lds = (LAS unsigned char*)lds_raw;
;     const Params& p = args.p;
;     const int tid = threadIdx.x, lane = tid & 63, wave = __builtin_amdgcn_readfirstlane(tid >> 6);
;     const int G = gridDim.x, gw = blockIdx.x * NWAVES + wave, ngw = G * NWAVES;
;     for (int u = tid; u < (LDS_BYTES - LDSCTL_OFF) / 4; u += NTHR) ((LAS unsigned*)(lds + LDSCTL_OFF))[u] = 0u;
;     __syncthreads();
_Z10hybrid_fwd4Args:
	s_load_dword s92, s[0:1], 0xd0
	v_writelane_b32 v240, s2, 0
	v_readfirstlane_b32 s2, v0
	v_lshl_add_u32 v1, v0, 2, 0
	v_add_u32_e32 v2, 0x20000, v1
	v_writelane_b32 v240, s2, 1
	s_cmp_lt_u32 s2, 0x100
	s_cbranch_scc1 .Lprio_skip
	s_setprio 1
